# attention V^T staging: adjacent lanes swap channel pairs via DPP + v_perm and write 8 ds_write_b32 instead of 16 ds_write_b16 (same LDS bytes); on top of v44
# baseline (speedup 1.0000x reference)
; #define LDS_BARRIER() asm volatile("s_waitcnt lgkmcnt(0)\n\ts_barrier" ::: "memory")
; __device__ __forceinline__ void attn_phase(LAS unsigned char* lds, const bf16_t* QKV, const float* kmean, const float* biasT, bf16_t* O, int G, int wg) {
;     ...
;         for (int ti = 0; ti < nTiles; ++ti) {
;             const bool own = ti < 4; const int r_ = ti - 4; const int blk = own ? ob : (r_ >> 2), kt = own ? ti : (r_ & 3);
;             const int key0 = blk * 256 + kt * 64;
;             LDS_BARRIER();
;             const int nxt = (cur == 2) ? 0 : cur + 1;
;             if (ti + 1 < nTiles) { ATT_STAGE(nxt); if (ti + 2 < nTiles) ATT_LOAD(ti + 2); }
.LBB0_1351:
	s_add_i32 s45, s59, 1
	s_cmp_lg_u32 s59, 2
	s_waitcnt lgkmcnt(0)
	s_barrier
	v_add_co_u32_e64 v128, s[0:1], s57, 4
	s_cselect_b32 s58, s45, 0
	s_add_i32 s45, s57, 5
	v_readfirstlane_b32 s44, v128
	s_cmp_ge_u32 s45, s55
	s_cbranch_scc1 .LBB0_1354
	s_mul_i32 s45, s58, 0x8800
	s_add_i32 s45, s45, 0
	v_add_u32_e32 v128, s45, v208
	v_add_u32_e32 v129, v128, v217
	v_add_u32_e32 v128, v128, v218
	s_waitcnt vmcnt(3)
	ds_write_b128 v128, v[96:99]
	v_add3_u32 v128, s45, v219, v220
	s_add_i32 s45, s57, 6
	s_cmp_ge_u32 s45, s55
	s_waitcnt vmcnt(2)
	ds_write_b128 v129, v[100:103]
	v_and_b32_e32 v96, 1, v213
	v_cmp_eq_u32_e64 s[48:49], 1, v96
	v_mul_u32_u24_e32 v96, 0x86, v96
	v_mov_b32_e32 v97, 0x5040100
	v_mov_b32_e32 v129, 0x3020706
	v_add_u32_e32 v128, v128, v96
	v_cndmask_b32_e64 v97, v97, v129, s[48:49]
	s_waitcnt vmcnt(1)
	v_mov_b32_dpp v98, v104 quad_perm:[1,0,3,2] row_mask:0xf bank_mask:0xf
	v_mov_b32_dpp v99, v105 quad_perm:[1,0,3,2] row_mask:0xf bank_mask:0xf
	v_mov_b32_dpp v100, v106 quad_perm:[1,0,3,2] row_mask:0xf bank_mask:0xf
	v_mov_b32_dpp v101, v107 quad_perm:[1,0,3,2] row_mask:0xf bank_mask:0xf
	v_perm_b32 v98, v98, v104, v97
	v_perm_b32 v99, v99, v105, v97
	v_perm_b32 v100, v100, v106, v97
	v_perm_b32 v101, v101, v107, v97
	ds_write_b32 v128, v98 offset:16384
	ds_write_b32 v128, v99 offset:16656
	ds_write_b32 v128, v100 offset:16928
	ds_write_b32 v128, v101 offset:17200
	s_waitcnt vmcnt(0)
	v_mov_b32_dpp v102, v108 quad_perm:[1,0,3,2] row_mask:0xf bank_mask:0xf
	v_mov_b32_dpp v103, v109 quad_perm:[1,0,3,2] row_mask:0xf bank_mask:0xf
	v_mov_b32_dpp v96, v110 quad_perm:[1,0,3,2] row_mask:0xf bank_mask:0xf
	v_mov_b32_dpp v129, v111 quad_perm:[1,0,3,2] row_mask:0xf bank_mask:0xf
	v_perm_b32 v102, v102, v108, v97
	v_perm_b32 v103, v103, v109, v97
	v_perm_b32 v96, v96, v110, v97
	v_perm_b32 v129, v129, v111, v97
	ds_write_b32 v128, v102 offset:17472
	ds_write_b32 v128, v103 offset:17744
	ds_write_b32 v128, v96 offset:18016
	ds_write_b32 v128, v129 offset:18288
	s_cbranch_scc1 .LBB0_1354
	s_add_i32 s48, s57, 2
	s_lshr_b32 s49, s48, 2
	s_and_b32 s48, s48, 3
	s_cmp_lt_u32 s44, 2
	s_cselect_b32 s44, s54, s49
	s_cselect_b32 s45, s45, s48
	s_lshl_b32 s44, s44, 8
	s_lshl_b32 s45, s45, 6
	s_add_i32 s44, s44, s45
	s_ashr_i32 s45, s44, 31
	s_add_u32 s44, s44, s46
	s_addc_u32 s45, s45, 0
	v_lshl_add_u64 v[96:97], s[44:45], 0, v[146:147]
	v_mad_u64_u32 v[100:101], s[48:49], v96, s89, v[184:185]
	v_mad_i32_i24 v101, v97, s89, v101
	v_or_b32_e32 v98, s44, v144
	v_mov_b64_e32 v[96:97], s[14:15]
	v_mad_u64_u32 v[96:97], s[48:49], v98, s89, v[96:97]
	v_mov_b32_e32 v98, 0x1800
	v_mad_i32_i24 v97, s45, v98, v97
	v_lshl_add_u64 v[96:97], v[96:97], 0, s[16:17]
	v_lshl_add_u64 v[104:105], v[148:149], 1, v[96:97]
	v_lshl_add_u64 v[108:109], v[104:105], 0, s[94:95]
	v_add_co_u32_e32 v104, vcc, 0x1000, v104
	global_load_dwordx4 v[96:99], v[100:101], off offset:2064
	s_nop 0
	global_load_dwordx4 v[100:103], v[100:101], off offset:2048
	v_addc_co_u32_e32 v105, vcc, 0, v105, vcc
	global_load_dwordx4 v[104:107], v[104:105], off
	s_nop 0
	global_load_dwordx4 v[108:111], v[108:109], off offset:16
